# code placement: the 16 GEMM K-loop heads aligned to 64 bytes, on top of the full stack
# speedup vs baseline: 1.0090x; 1.0023x over previous
; template <class Epi, class Sched, bool ALIGN_EPI = false, bool SP2 = false>
; __device__ __forceinline__ void gemm_phase(PG8_LAS unsigned char* lds, const Gemm g, const Sched& S, const Epi& E) {
;     ...
;     f32x4 acc[2][2][4][2];
; #pragma unroll
;     for (int a = 0; a < 2; ++a)
; #pragma unroll
;         for (int b = 0; b < 2; ++b)
; #pragma unroll
;             for (int m = 0; m < 4; ++m)
; #pragma unroll
;                 for (int n = 0; n < 2; ++n) acc[a][b][m][n] = (f32x4){0.f, 0.f, 0.f, 0.f};
;     ...
;         const bool has_next = S.next(ui + 1, nxt);
;         const char* nA = has_next ? (const char*)g.A + (size_t)nxt.pm * tstepA : cA; const char* nB = has_next ? (const char*)g.Bt + (size_t)nxt.pn * tstepB : cB;
;         for (int t = 0; t < nt; t += 2) {
.LBB0_370:
	s_ashr_i32 s25, s24, 31
	s_lshl_b64 s[0:1], s[24:25], 20
	s_add_u32 s26, s33, s0
	s_addc_u32 s27, s44, s1
	s_and_b64 s[0:1], s[6:7], exec
	s_cselect_b32 s0, s27, s9
	s_cselect_b32 s1, s26, s8
	s_ashr_i32 s23, s22, 31
	s_lshl_b64 s[28:29], s[22:23], 20
	s_add_u32 s28, s45, s28
	s_addc_u32 s29, s46, s29
	s_and_b64 s[38:39], s[6:7], exec
	s_cselect_b32 s23, s29, s37
	s_cselect_b32 s25, s28, s36
	s_add_u32 s31, s1, 0x80
	s_addc_u32 s69, s0, 0
	s_add_u32 s70, s36, 0x100
	v_mov_b32_e32 v0, 0
	s_addc_u32 s71, s37, 0
	s_mov_b32 s72, -2
	s_mov_b32 s73, 0x18000
	s_mov_b64 s[36:37], 0
	v_mov_b32_e32 v1, v0
	v_mov_b32_e32 v2, v0
	v_mov_b32_e32 v3, v0
	v_mov_b32_e32 v8, v0
	v_mov_b32_e32 v9, v0
	s_waitcnt vmcnt(22)
	v_mov_b32_e32 v10, v0
	v_mov_b32_e32 v11, v0
	s_waitcnt vmcnt(21)
	v_mov_b32_e32 v16, v0
	v_mov_b32_e32 v17, v0
	s_waitcnt vmcnt(20)
	v_mov_b32_e32 v18, v0
	v_mov_b32_e32 v19, v0
	s_waitcnt vmcnt(19)
	v_mov_b32_e32 v24, v0
	v_mov_b32_e32 v25, v0
	s_waitcnt vmcnt(18)
	v_mov_b32_e32 v26, v0
	v_mov_b32_e32 v27, v0
	s_waitcnt vmcnt(17)
	v_mov_b32_e32 v32, v0
	v_mov_b32_e32 v33, v0
	s_waitcnt vmcnt(16)
	v_mov_b32_e32 v34, v0
	v_mov_b32_e32 v35, v0
	s_waitcnt vmcnt(15)
	v_mov_b32_e32 v40, v0
	v_mov_b32_e32 v41, v0
	s_waitcnt vmcnt(14)
	v_mov_b32_e32 v42, v0
	v_mov_b32_e32 v43, v0
	s_waitcnt vmcnt(13)
	v_mov_b32_e32 v48, v0
	v_mov_b32_e32 v49, v0
	s_waitcnt vmcnt(12)
	v_mov_b32_e32 v50, v0
	v_mov_b32_e32 v51, v0
	s_waitcnt vmcnt(11)
	v_mov_b32_e32 v56, v0
	v_mov_b32_e32 v57, v0
	s_waitcnt vmcnt(10)
	v_mov_b32_e32 v58, v0
	v_mov_b32_e32 v59, v0
	v_mov_b32_e32 v4, v0
	v_mov_b32_e32 v5, v0
	v_mov_b32_e32 v6, v0
	v_mov_b32_e32 v7, v0
	v_mov_b32_e32 v12, v0
	v_mov_b32_e32 v13, v0
	v_mov_b32_e32 v14, v0
	v_mov_b32_e32 v15, v0
	v_mov_b32_e32 v20, v0
	v_mov_b32_e32 v21, v0
	v_mov_b32_e32 v22, v0
	v_mov_b32_e32 v23, v0
	v_mov_b32_e32 v28, v0
	v_mov_b32_e32 v29, v0
	v_mov_b32_e32 v30, v0
	v_mov_b32_e32 v31, v0
	v_mov_b32_e32 v36, v0
	v_mov_b32_e32 v37, v0
	v_mov_b32_e32 v38, v0
	v_mov_b32_e32 v39, v0
	v_mov_b32_e32 v44, v0
	v_mov_b32_e32 v45, v0
	v_mov_b32_e32 v46, v0
	v_mov_b32_e32 v47, v0
	v_mov_b32_e32 v52, v0
	v_mov_b32_e32 v53, v0
	v_mov_b32_e32 v54, v0
	v_mov_b32_e32 v55, v0
	v_mov_b32_e32 v60, v0
	v_mov_b32_e32 v61, v0
	s_waitcnt vmcnt(9)
	v_mov_b32_e32 v62, v0
	v_mov_b32_e32 v63, v0
	v_mov_b32_e32 v64, v0
	v_mov_b32_e32 v65, v0
	s_waitcnt vmcnt(8)
	v_mov_b32_e32 v66, v0
	v_mov_b32_e32 v67, v0
	v_mov_b32_e32 v72, v0
	v_mov_b32_e32 v73, v0
	v_mov_b32_e32 v74, v0
	v_mov_b32_e32 v75, v0
	v_mov_b32_e32 v80, v0
	v_mov_b32_e32 v81, v0
	v_mov_b32_e32 v82, v0
	v_mov_b32_e32 v83, v0
	v_mov_b32_e32 v88, v0
	v_mov_b32_e32 v89, v0
	v_mov_b32_e32 v90, v0
	v_mov_b32_e32 v91, v0
	v_mov_b32_e32 v96, v0
	v_mov_b32_e32 v97, v0
	v_mov_b32_e32 v98, v0
	v_mov_b32_e32 v99, v0
	v_mov_b32_e32 v104, v0
	v_mov_b32_e32 v105, v0
	v_mov_b32_e32 v106, v0
	v_mov_b32_e32 v107, v0
	v_mov_b32_e32 v112, v0
	v_mov_b32_e32 v113, v0
	v_mov_b32_e32 v114, v0
	v_mov_b32_e32 v115, v0
	v_mov_b32_e32 v120, v0
	v_mov_b32_e32 v121, v0
	v_mov_b32_e32 v122, v0
	v_mov_b32_e32 v123, v0
	v_mov_b32_e32 v68, v0
	v_mov_b32_e32 v69, v0
	v_mov_b32_e32 v70, v0
	v_mov_b32_e32 v71, v0
	v_mov_b32_e32 v76, v0
	v_mov_b32_e32 v77, v0
	v_mov_b32_e32 v78, v0
	v_mov_b32_e32 v79, v0
	v_mov_b32_e32 v84, v0
	v_mov_b32_e32 v85, v0
	v_mov_b32_e32 v86, v0
	v_mov_b32_e32 v87, v0
	v_mov_b32_e32 v92, v0
	v_mov_b32_e32 v93, v0
	v_mov_b32_e32 v94, v0
	v_mov_b32_e32 v95, v0
	v_mov_b32_e32 v100, v0
	v_mov_b32_e32 v101, v0
	v_mov_b32_e32 v102, v0
	v_mov_b32_e32 v103, v0
	v_mov_b32_e32 v108, v0
	v_mov_b32_e32 v109, v0
	v_mov_b32_e32 v110, v0
	v_mov_b32_e32 v111, v0
	v_mov_b32_e32 v116, v0
	v_mov_b32_e32 v117, v0
	v_mov_b32_e32 v118, v0
	v_mov_b32_e32 v119, v0
	v_mov_b32_e32 v124, v0
	v_mov_b32_e32 v125, v0
	v_mov_b32_e32 v126, v0
	v_mov_b32_e32 v127, v0
	.p2align	6

; template <class Epi, class Sched, bool ALIGN_EPI = false, bool SP2 = false>
; __device__ __forceinline__ void gemm_phase(PG8_LAS unsigned char* lds, const Gemm g, const Sched& S, const Epi& E) {
;     ...
;             const char* a2 = last ? nA : cA + PG8_KOFFA(t + 2); const char* b2 = last ? nB : cB + (size_t)(t + 2) * kstep;
;             const char* a3 = last ? nA + kstep : cA + PG8_KOFFA(t + 3); const char* b3 = b2 + kstep;
;     ...
; #pragma unroll
;         for (int a = 0; a < 2; ++a)
; #pragma unroll
;             for (int b = 0; b < 2; ++b)
; #pragma unroll
;                 for (int m = 0; m < 4; ++m)
; #pragma unroll
;                     for (int n = 0; n < 2; ++n) acc[a][b][m][n] = (f32x4){0.f, 0.f, 0.f, 0.f};
.LBB0_510:
	s_add_u32 s0, s28, 0x100
	v_mov_b32_e32 v0, 0
	s_addc_u32 s1, s29, 0
	s_mov_b32 s64, -2
	s_waitcnt lgkmcnt(0)
	v_mov_b32_e32 v1, v0
	v_mov_b32_e32 v2, v0
	v_mov_b32_e32 v3, v0
	v_mov_b32_e32 v4, v0
	v_mov_b32_e32 v5, v0
	v_mov_b32_e32 v6, v0
	v_mov_b32_e32 v7, v0
	s_waitcnt vmcnt(21)
	v_mov_b32_e32 v16, v0
	v_mov_b32_e32 v17, v0
	s_waitcnt vmcnt(20)
	v_mov_b32_e32 v18, v0
	v_mov_b32_e32 v19, v0
	v_mov_b32_e32 v20, v0
	v_mov_b32_e32 v21, v0
	s_waitcnt vmcnt(19)
	v_mov_b32_e32 v22, v0
	v_mov_b32_e32 v23, v0
	s_waitcnt vmcnt(17)
	v_mov_b32_e32 v32, v0
	v_mov_b32_e32 v33, v0
	s_waitcnt vmcnt(16)
	v_mov_b32_e32 v34, v0
	v_mov_b32_e32 v35, v0
	v_mov_b32_e32 v36, v0
	v_mov_b32_e32 v37, v0
	s_waitcnt vmcnt(15)
	v_mov_b32_e32 v38, v0
	v_mov_b32_e32 v39, v0
	s_waitcnt vmcnt(13)
	v_mov_b32_e32 v48, v0
	v_mov_b32_e32 v49, v0
	s_waitcnt vmcnt(12)
	v_mov_b32_e32 v50, v0
	v_mov_b32_e32 v51, v0
	v_mov_b32_e32 v52, v0
	v_mov_b32_e32 v53, v0
	s_waitcnt vmcnt(11)
	v_mov_b32_e32 v54, v0
	v_mov_b32_e32 v55, v0
	v_mov_b32_e32 v8, v0
	v_mov_b32_e32 v9, v0
	v_mov_b32_e32 v10, v0
	v_mov_b32_e32 v11, v0
	v_mov_b32_e32 v12, v0
	v_mov_b32_e32 v13, v0
	v_mov_b32_e32 v14, v0
	v_mov_b32_e32 v15, v0
	v_mov_b32_e32 v24, v0
	v_mov_b32_e32 v25, v0
	v_mov_b32_e32 v26, v0
	v_mov_b32_e32 v27, v0
	v_mov_b32_e32 v28, v0
	v_mov_b32_e32 v29, v0
	v_mov_b32_e32 v30, v0
	v_mov_b32_e32 v31, v0
	v_mov_b32_e32 v40, v0
	v_mov_b32_e32 v41, v0
	v_mov_b32_e32 v42, v0
	v_mov_b32_e32 v43, v0
	v_mov_b32_e32 v44, v0
	v_mov_b32_e32 v45, v0
	v_mov_b32_e32 v46, v0
	v_mov_b32_e32 v47, v0
	v_mov_b32_e32 v56, v0
	v_mov_b32_e32 v57, v0
	s_waitcnt vmcnt(10)
	v_mov_b32_e32 v58, v0
	v_mov_b32_e32 v59, v0
	v_mov_b32_e32 v60, v0
	v_mov_b32_e32 v61, v0
	s_waitcnt vmcnt(9)
	v_mov_b32_e32 v62, v0
	v_mov_b32_e32 v63, v0
	v_mov_b32_e32 v64, v0
	v_mov_b32_e32 v65, v0
	s_waitcnt vmcnt(8)
	v_mov_b32_e32 v66, v0
	v_mov_b32_e32 v67, v0
	v_mov_b32_e32 v68, v0
	v_mov_b32_e32 v69, v0
	v_mov_b32_e32 v70, v0
	v_mov_b32_e32 v71, v0
	v_mov_b32_e32 v80, v0
	v_mov_b32_e32 v81, v0
	v_mov_b32_e32 v82, v0
	v_mov_b32_e32 v83, v0
	v_mov_b32_e32 v84, v0
	v_mov_b32_e32 v85, v0
	v_mov_b32_e32 v86, v0
	v_mov_b32_e32 v87, v0
	v_mov_b32_e32 v96, v0
	v_mov_b32_e32 v97, v0
	v_mov_b32_e32 v98, v0
	v_mov_b32_e32 v99, v0
	v_mov_b32_e32 v100, v0
	v_mov_b32_e32 v101, v0
	v_mov_b32_e32 v102, v0
	v_mov_b32_e32 v103, v0
	v_mov_b32_e32 v112, v0
	v_mov_b32_e32 v113, v0
	v_mov_b32_e32 v114, v0
	v_mov_b32_e32 v115, v0
	v_mov_b32_e32 v116, v0
	v_mov_b32_e32 v117, v0
	v_mov_b32_e32 v118, v0
	v_mov_b32_e32 v119, v0
	v_mov_b32_e32 v72, v0
	v_mov_b32_e32 v73, v0
	v_mov_b32_e32 v74, v0
	v_mov_b32_e32 v75, v0
	v_mov_b32_e32 v76, v0
	v_mov_b32_e32 v77, v0
	v_mov_b32_e32 v78, v0
	v_mov_b32_e32 v79, v0
	v_mov_b32_e32 v88, v0
	v_mov_b32_e32 v89, v0
	v_mov_b32_e32 v90, v0
	v_mov_b32_e32 v91, v0
	v_mov_b32_e32 v92, v0
	v_mov_b32_e32 v93, v0
	v_mov_b32_e32 v94, v0
	v_mov_b32_e32 v95, v0
	v_mov_b32_e32 v104, v0
	v_mov_b32_e32 v105, v0
	v_mov_b32_e32 v106, v0
	v_mov_b32_e32 v107, v0
	v_mov_b32_e32 v108, v0
	v_mov_b32_e32 v109, v0
	v_mov_b32_e32 v110, v0
	v_mov_b32_e32 v111, v0
	v_mov_b32_e32 v120, v0
	v_mov_b32_e32 v121, v0
	v_mov_b32_e32 v122, v0
	v_mov_b32_e32 v123, v0
	v_mov_b32_e32 v124, v0
	v_mov_b32_e32 v125, v0
	v_mov_b32_e32 v126, v0
	v_mov_b32_e32 v127, v0
	.p2align	6

; template <class Epi, class Sched, bool ALIGN_EPI = false, bool SP2 = false>
; __device__ __forceinline__ void gemm_phase(PG8_LAS unsigned char* lds, const Gemm g, const Sched& S, const Epi& E) {
;     ...
;         const char* nA = has_next ? (const char*)g.A + (size_t)nxt.pm * tstepA : cA; const char* nB = has_next ? (const char*)g.Bt + (size_t)nxt.pn * tstepB : cB;
;         for (int t = 0; t < nt; t += 2) {
;             const bool last = (t == nt - 2);
;     ...
;             const char* a1 = cA + PG8_KOFFA(t + 1);
;             const char* a2 = last ? nA : cA + PG8_KOFFA(t + 2); const char* b2 = last ? nB : cB + (size_t)(t + 2) * kstep;
;             const char* a3 = last ? nA + kstep : cA + PG8_KOFFA(t + 3); const char* b3 = b2 + kstep;
;     ...
; #pragma unroll
;         for (int a = 0; a < 2; ++a)
; #pragma unroll
;             for (int b = 0; b < 2; ++b)
; #pragma unroll
;                 for (int m = 0; m < 4; ++m)
; #pragma unroll
;                     for (int n = 0; n < 2; ++n) acc[a][b][m][n] = (f32x4){0.f, 0.f, 0.f, 0.f};
.LBB0_631:
	s_ashr_i32 s45, s44, 31
	s_lshl_b64 s[0:1], s[44:45], 20
	s_add_u32 s46, s31, s0
	s_addc_u32 s47, s33, s1
	s_and_b64 s[0:1], s[8:9], exec
	s_cselect_b32 s0, s47, s11
	s_cselect_b32 s1, s46, s10
	s_ashr_i32 s43, s42, 31
	s_lshl_b64 s[4:5], s[42:43], 20
	s_add_u32 s48, s35, s4
	s_addc_u32 s49, s37, s5
	s_and_b64 s[4:5], s[8:9], exec
	s_cselect_b32 s4, s49, s53
	s_cselect_b32 s5, s48, s52
	s_add_u32 s16, s1, 0x80
	s_addc_u32 s43, s0, 0
	s_add_u32 s45, s52, 0x100
	v_mov_b32_e32 v0, 0
	s_addc_u32 s51, s53, 0
	s_mov_b32 s55, -2
	s_mov_b32 s84, 0x18000
	s_mov_b64 s[52:53], 0
	v_mov_b32_e32 v1, v0
	s_waitcnt lgkmcnt(1)
	v_mov_b32_e32 v2, v0
	s_waitcnt lgkmcnt(0)
	v_mov_b32_e32 v3, v0
	v_mov_b32_e32 v4, v0
	v_mov_b32_e32 v5, v0
	v_mov_b32_e32 v6, v0
	v_mov_b32_e32 v7, v0
	s_waitcnt vmcnt(21)
	v_mov_b32_e32 v16, v0
	v_mov_b32_e32 v17, v0
	s_waitcnt vmcnt(20)
	v_mov_b32_e32 v18, v0
	v_mov_b32_e32 v19, v0
	v_mov_b32_e32 v20, v0
	v_mov_b32_e32 v21, v0
	s_waitcnt vmcnt(19)
	v_mov_b32_e32 v22, v0
	v_mov_b32_e32 v23, v0
	s_waitcnt vmcnt(17)
	v_mov_b32_e32 v32, v0
	v_mov_b32_e32 v33, v0
	s_waitcnt vmcnt(16)
	v_mov_b32_e32 v34, v0
	v_mov_b32_e32 v35, v0
	v_mov_b32_e32 v36, v0
	v_mov_b32_e32 v37, v0
	s_waitcnt vmcnt(15)
	v_mov_b32_e32 v38, v0
	v_mov_b32_e32 v39, v0
	s_waitcnt vmcnt(13)
	v_mov_b32_e32 v48, v0
	v_mov_b32_e32 v49, v0
	s_waitcnt vmcnt(12)
	v_mov_b32_e32 v50, v0
	v_mov_b32_e32 v51, v0
	v_mov_b32_e32 v52, v0
	v_mov_b32_e32 v53, v0
	s_waitcnt vmcnt(11)
	v_mov_b32_e32 v54, v0
	v_mov_b32_e32 v55, v0
	v_mov_b32_e32 v8, v0
	v_mov_b32_e32 v9, v0
	v_mov_b32_e32 v10, v0
	v_mov_b32_e32 v11, v0
	v_mov_b32_e32 v12, v0
	v_mov_b32_e32 v13, v0
	v_mov_b32_e32 v14, v0
	v_mov_b32_e32 v15, v0
	v_mov_b32_e32 v24, v0
	v_mov_b32_e32 v25, v0
	v_mov_b32_e32 v26, v0
	v_mov_b32_e32 v27, v0
	v_mov_b32_e32 v28, v0
	v_mov_b32_e32 v29, v0
	v_mov_b32_e32 v30, v0
	v_mov_b32_e32 v31, v0
	v_mov_b32_e32 v40, v0
	v_mov_b32_e32 v41, v0
	v_mov_b32_e32 v42, v0
	v_mov_b32_e32 v43, v0
	v_mov_b32_e32 v44, v0
	v_mov_b32_e32 v45, v0
	v_mov_b32_e32 v46, v0
	v_mov_b32_e32 v47, v0
	v_mov_b32_e32 v56, v0
	v_mov_b32_e32 v57, v0
	s_waitcnt vmcnt(10)
	v_mov_b32_e32 v58, v0
	v_mov_b32_e32 v59, v0
	v_mov_b32_e32 v60, v0
	v_mov_b32_e32 v61, v0
	s_waitcnt vmcnt(9)
	v_mov_b32_e32 v62, v0
	v_mov_b32_e32 v63, v0
	v_mov_b32_e32 v64, v0
	v_mov_b32_e32 v65, v0
	s_waitcnt vmcnt(8)
	v_mov_b32_e32 v66, v0
	v_mov_b32_e32 v67, v0
	v_mov_b32_e32 v68, v0
	v_mov_b32_e32 v69, v0
	v_mov_b32_e32 v70, v0
	v_mov_b32_e32 v71, v0
	v_mov_b32_e32 v80, v0
	v_mov_b32_e32 v81, v0
	v_mov_b32_e32 v82, v0
	v_mov_b32_e32 v83, v0
	v_mov_b32_e32 v84, v0
	v_mov_b32_e32 v85, v0
	v_mov_b32_e32 v86, v0
	v_mov_b32_e32 v87, v0
	v_mov_b32_e32 v96, v0
	v_mov_b32_e32 v97, v0
	v_mov_b32_e32 v98, v0
	v_mov_b32_e32 v99, v0
	v_mov_b32_e32 v100, v0
	v_mov_b32_e32 v101, v0
	v_mov_b32_e32 v102, v0
	v_mov_b32_e32 v103, v0
	v_mov_b32_e32 v112, v0
	v_mov_b32_e32 v113, v0
	v_mov_b32_e32 v114, v0
	v_mov_b32_e32 v115, v0
	v_mov_b32_e32 v116, v0
	v_mov_b32_e32 v117, v0
	v_mov_b32_e32 v118, v0
	v_mov_b32_e32 v119, v0
	v_mov_b32_e32 v72, v0
	v_mov_b32_e32 v73, v0
	v_mov_b32_e32 v74, v0
	v_mov_b32_e32 v75, v0
	v_mov_b32_e32 v76, v0
	v_mov_b32_e32 v77, v0
	v_mov_b32_e32 v78, v0
	v_mov_b32_e32 v79, v0
	v_mov_b32_e32 v88, v0
	v_mov_b32_e32 v89, v0
	v_mov_b32_e32 v90, v0
	v_mov_b32_e32 v91, v0
	v_mov_b32_e32 v92, v0
	v_mov_b32_e32 v93, v0
	v_mov_b32_e32 v94, v0
	v_mov_b32_e32 v95, v0
	v_mov_b32_e32 v104, v0
	v_mov_b32_e32 v105, v0
	v_mov_b32_e32 v106, v0
	v_mov_b32_e32 v107, v0
	v_mov_b32_e32 v108, v0
	v_mov_b32_e32 v109, v0
	v_mov_b32_e32 v110, v0
	v_mov_b32_e32 v111, v0
	v_mov_b32_e32 v120, v0
	v_mov_b32_e32 v121, v0
	v_mov_b32_e32 v122, v0
	v_mov_b32_e32 v123, v0
	v_mov_b32_e32 v124, v0
	v_mov_b32_e32 v125, v0
	v_mov_b32_e32 v126, v0
	v_mov_b32_e32 v127, v0
	.p2align	6

; template <class Epi, class Sched, bool ALIGN_EPI = false, bool SP2 = false>
; __device__ __forceinline__ void gemm_phase(PG8_LAS unsigned char* lds, const Gemm g, const Sched& S, const Epi& E) {
;     ...
;         const char* nA = has_next ? (const char*)g.A + (size_t)nxt.pm * tstepA : cA; const char* nB = has_next ? (const char*)g.Bt + (size_t)nxt.pn * tstepB : cB;
;         for (int t = 0; t < nt; t += 2) {
;             const bool last = (t == nt - 2);
;     ...
;             const char* a1 = cA + PG8_KOFFA(t + 1);
;             const char* a2 = last ? nA : cA + PG8_KOFFA(t + 2); const char* b2 = last ? nB : cB + (size_t)(t + 2) * kstep;
;             const char* a3 = last ? nA + kstep : cA + PG8_KOFFA(t + 3); const char* b3 = b2 + kstep;
;     ...
; #pragma unroll
;         for (int a = 0; a < 2; ++a)
; #pragma unroll
;             for (int b = 0; b < 2; ++b)
; #pragma unroll
;                 for (int m = 0; m < 4; ++m)
; #pragma unroll
;                     for (int n = 0; n < 2; ++n) acc[a][b][m][n] = (f32x4){0.f, 0.f, 0.f, 0.f};
.LBB0_839:
	s_ashr_i32 s27, s26, 31
	s_lshl_b64 s[0:1], s[26:27], 22
	s_add_u32 s28, s5, s0
	s_addc_u32 s29, s33, s1
	s_and_b64 s[0:1], s[8:9], exec
	s_cselect_b32 s0, s29, s41
	s_cselect_b32 s1, s28, s40
	s_ashr_i32 s25, s24, 31
	s_lshl_b64 s[30:31], s[24:25], 21
	s_add_u32 s30, s50, s30
	s_addc_u32 s31, s51, s31
	s_and_b64 s[42:43], s[8:9], exec
	s_cselect_b32 s25, s31, s39
	s_cselect_b32 s27, s30, s38
	s_add_u32 s37, s1, 0x80
	v_mov_b32_e32 v0, 0
	s_addc_u32 s71, s0, 0
	s_mov_b32 s44, -2
	s_mov_b64 s[42:43], 0x100
	s_waitcnt lgkmcnt(0)
	v_mov_b32_e32 v1, v0
	v_mov_b32_e32 v2, v0
	v_mov_b32_e32 v3, v0
	v_mov_b32_e32 v4, v0
	v_mov_b32_e32 v5, v0
	s_waitcnt vmcnt(23)
	v_mov_b32_e32 v6, v0
	v_mov_b32_e32 v7, v0
	s_waitcnt vmcnt(21)
	v_mov_b32_e32 v16, v0
	v_mov_b32_e32 v17, v0
	s_waitcnt vmcnt(20)
	v_mov_b32_e32 v18, v0
	v_mov_b32_e32 v19, v0
	v_mov_b32_e32 v20, v0
	v_mov_b32_e32 v21, v0
	s_waitcnt vmcnt(19)
	v_mov_b32_e32 v22, v0
	v_mov_b32_e32 v23, v0
	s_waitcnt vmcnt(17)
	v_mov_b32_e32 v32, v0
	v_mov_b32_e32 v33, v0
	s_waitcnt vmcnt(16)
	v_mov_b32_e32 v34, v0
	v_mov_b32_e32 v35, v0
	v_mov_b32_e32 v36, v0
	v_mov_b32_e32 v37, v0
	s_waitcnt vmcnt(15)
	v_mov_b32_e32 v38, v0
	v_mov_b32_e32 v39, v0
	s_waitcnt vmcnt(13)
	v_mov_b32_e32 v48, v0
	v_mov_b32_e32 v49, v0
	s_waitcnt vmcnt(12)
	v_mov_b32_e32 v50, v0
	v_mov_b32_e32 v51, v0
	v_mov_b32_e32 v52, v0
	v_mov_b32_e32 v53, v0
	s_waitcnt vmcnt(11)
	v_mov_b32_e32 v54, v0
	v_mov_b32_e32 v55, v0
	v_mov_b32_e32 v8, v0
	v_mov_b32_e32 v9, v0
	v_mov_b32_e32 v10, v0
	v_mov_b32_e32 v11, v0
	v_mov_b32_e32 v12, v0
	v_mov_b32_e32 v13, v0
	v_mov_b32_e32 v14, v0
	v_mov_b32_e32 v15, v0
	v_mov_b32_e32 v24, v0
	v_mov_b32_e32 v25, v0
	v_mov_b32_e32 v26, v0
	v_mov_b32_e32 v27, v0
	v_mov_b32_e32 v28, v0
	v_mov_b32_e32 v29, v0
	v_mov_b32_e32 v30, v0
	v_mov_b32_e32 v31, v0
	v_mov_b32_e32 v40, v0
	v_mov_b32_e32 v41, v0
	v_mov_b32_e32 v42, v0
	v_mov_b32_e32 v43, v0
	v_mov_b32_e32 v44, v0
	v_mov_b32_e32 v45, v0
	v_mov_b32_e32 v46, v0
	v_mov_b32_e32 v47, v0
	v_mov_b32_e32 v56, v0
	v_mov_b32_e32 v57, v0
	s_waitcnt vmcnt(10)
	v_mov_b32_e32 v58, v0
	v_mov_b32_e32 v59, v0
	v_mov_b32_e32 v60, v0
	v_mov_b32_e32 v61, v0
	s_waitcnt vmcnt(9)
	v_mov_b32_e32 v62, v0
	v_mov_b32_e32 v63, v0
	v_mov_b32_e32 v64, v0
	v_mov_b32_e32 v65, v0
	s_waitcnt vmcnt(8)
	v_mov_b32_e32 v66, v0
	v_mov_b32_e32 v67, v0
	v_mov_b32_e32 v68, v0
	v_mov_b32_e32 v69, v0
	v_mov_b32_e32 v70, v0
	v_mov_b32_e32 v71, v0
	v_mov_b32_e32 v80, v0
	v_mov_b32_e32 v81, v0
	v_mov_b32_e32 v82, v0
	v_mov_b32_e32 v83, v0
	v_mov_b32_e32 v84, v0
	v_mov_b32_e32 v85, v0
	v_mov_b32_e32 v86, v0
	v_mov_b32_e32 v87, v0
	v_mov_b32_e32 v96, v0
	v_mov_b32_e32 v97, v0
	v_mov_b32_e32 v98, v0
	v_mov_b32_e32 v99, v0
	v_mov_b32_e32 v100, v0
	v_mov_b32_e32 v101, v0
	v_mov_b32_e32 v102, v0
	v_mov_b32_e32 v103, v0
	v_mov_b32_e32 v120, v0
	v_mov_b32_e32 v121, v0
	v_mov_b32_e32 v122, v0
	v_mov_b32_e32 v123, v0
	v_mov_b32_e32 v124, v0
	v_mov_b32_e32 v125, v0
	v_mov_b32_e32 v126, v0
	v_mov_b32_e32 v127, v0
	v_mov_b32_e32 v72, v0
	v_mov_b32_e32 v73, v0
	v_mov_b32_e32 v74, v0
	v_mov_b32_e32 v75, v0
	v_mov_b32_e32 v76, v0
	v_mov_b32_e32 v77, v0
	v_mov_b32_e32 v78, v0
	v_mov_b32_e32 v79, v0
	v_mov_b32_e32 v88, v0
	v_mov_b32_e32 v89, v0
	v_mov_b32_e32 v90, v0
	v_mov_b32_e32 v91, v0
	v_mov_b32_e32 v92, v0
	v_mov_b32_e32 v93, v0
	v_mov_b32_e32 v94, v0
	v_mov_b32_e32 v95, v0
	v_mov_b32_e32 v108, v0
	v_mov_b32_e32 v109, v0
	v_mov_b32_e32 v110, v0
	v_mov_b32_e32 v111, v0
	v_mov_b32_e32 v112, v0
	v_mov_b32_e32 v113, v0
	v_mov_b32_e32 v114, v0
	v_mov_b32_e32 v115, v0
	v_mov_b32_e32 v132, v0
	v_mov_b32_e32 v133, v0
	v_mov_b32_e32 v134, v0
	v_mov_b32_e32 v135, v0
	v_mov_b32_e32 v136, v0
	v_mov_b32_e32 v137, v0
	v_mov_b32_e32 v138, v0
	v_mov_b32_e32 v139, v0
	.p2align	6

; template <class Epi, class Sched, bool ALIGN_EPI = false, bool SP2 = false>
; __device__ __forceinline__ void gemm_phase(PG8_LAS unsigned char* lds, const Gemm g, const Sched& S, const Epi& E) {
;     ...
;         const char* nA = has_next ? (const char*)g.A + (size_t)nxt.pm * tstepA : cA; const char* nB = has_next ? (const char*)g.Bt + (size_t)nxt.pn * tstepB : cB;
;         for (int t = 0; t < nt; t += 2) {
;             const bool last = (t == nt - 2);
;     ...
;             const char* a1 = cA + PG8_KOFFA(t + 1);
;             const char* a2 = last ? nA : cA + PG8_KOFFA(t + 2); const char* b2 = last ? nB : cB + (size_t)(t + 2) * kstep;
;             const char* a3 = last ? nA + kstep : cA + PG8_KOFFA(t + 3); const char* b3 = b2 + kstep;
;     ...
; #pragma unroll
;         for (int a = 0; a < 2; ++a)
; #pragma unroll
;             for (int b = 0; b < 2; ++b)
; #pragma unroll
;                 for (int m = 0; m < 4; ++m)
; #pragma unroll
;                     for (int n = 0; n < 2; ++n) acc[a][b][m][n] = (f32x4){0.f, 0.f, 0.f, 0.f};
.LBB0_952:
	s_ashr_i32 s23, s22, 31
	s_lshl_b64 s[0:1], s[22:23], 20
	s_add_u32 s24, s5, s0
	s_addc_u32 s25, s42, s1
	s_and_b64 s[0:1], s[6:7], exec
	s_cselect_b32 s0, s25, s9
	s_cselect_b32 s1, s24, s8
	s_ashr_i32 s21, s20, 31
	s_lshl_b64 s[26:27], s[20:21], 20
	s_add_u32 s26, s43, s26
	s_addc_u32 s27, s44, s27
	s_and_b64 s[36:37], s[6:7], exec
	s_cselect_b32 s21, s27, s35
	s_cselect_b32 s23, s26, s34
	s_add_u32 s29, s1, 0x80
	s_addc_u32 s67, s0, 0
	s_add_u32 s68, s34, 0x100
	v_mov_b32_e32 v0, 0
	s_addc_u32 s69, s35, 0
	s_mov_b32 s70, -2
	s_mov_b32 s71, 0x18000
	s_mov_b64 s[34:35], 0
	v_mov_b32_e32 v1, v0
	v_mov_b32_e32 v2, v0
	v_mov_b32_e32 v3, v0
	s_waitcnt vmcnt(23)
	v_mov_b32_e32 v8, v0
	v_mov_b32_e32 v9, v0
	s_waitcnt vmcnt(22)
	v_mov_b32_e32 v10, v0
	v_mov_b32_e32 v11, v0
	s_waitcnt vmcnt(21)
	v_mov_b32_e32 v16, v0
	v_mov_b32_e32 v17, v0
	s_waitcnt vmcnt(20)
	v_mov_b32_e32 v18, v0
	v_mov_b32_e32 v19, v0
	s_waitcnt vmcnt(19)
	v_mov_b32_e32 v24, v0
	v_mov_b32_e32 v25, v0
	s_waitcnt vmcnt(18)
	v_mov_b32_e32 v26, v0
	v_mov_b32_e32 v27, v0
	s_waitcnt vmcnt(17)
	v_mov_b32_e32 v32, v0
	v_mov_b32_e32 v33, v0
	s_waitcnt vmcnt(16)
	v_mov_b32_e32 v34, v0
	v_mov_b32_e32 v35, v0
	s_waitcnt vmcnt(15)
	v_mov_b32_e32 v40, v0
	v_mov_b32_e32 v41, v0
	s_waitcnt vmcnt(14)
	v_mov_b32_e32 v42, v0
	v_mov_b32_e32 v43, v0
	s_waitcnt vmcnt(13)
	v_mov_b32_e32 v48, v0
	v_mov_b32_e32 v49, v0
	s_waitcnt vmcnt(12)
	v_mov_b32_e32 v50, v0
	v_mov_b32_e32 v51, v0
	s_waitcnt vmcnt(11)
	v_mov_b32_e32 v56, v0
	v_mov_b32_e32 v57, v0
	s_waitcnt vmcnt(10)
	v_mov_b32_e32 v58, v0
	v_mov_b32_e32 v59, v0
	v_mov_b32_e32 v4, v0
	v_mov_b32_e32 v5, v0
	v_mov_b32_e32 v6, v0
	v_mov_b32_e32 v7, v0
	v_mov_b32_e32 v12, v0
	v_mov_b32_e32 v13, v0
	v_mov_b32_e32 v14, v0
	v_mov_b32_e32 v15, v0
	v_mov_b32_e32 v20, v0
	v_mov_b32_e32 v21, v0
	v_mov_b32_e32 v22, v0
	v_mov_b32_e32 v23, v0
	v_mov_b32_e32 v28, v0
	v_mov_b32_e32 v29, v0
	v_mov_b32_e32 v30, v0
	v_mov_b32_e32 v31, v0
	v_mov_b32_e32 v36, v0
	v_mov_b32_e32 v37, v0
	v_mov_b32_e32 v38, v0
	v_mov_b32_e32 v39, v0
	v_mov_b32_e32 v44, v0
	v_mov_b32_e32 v45, v0
	v_mov_b32_e32 v46, v0
	v_mov_b32_e32 v47, v0
	v_mov_b32_e32 v52, v0
	v_mov_b32_e32 v53, v0
	v_mov_b32_e32 v54, v0
	v_mov_b32_e32 v55, v0
	v_mov_b32_e32 v60, v0
	v_mov_b32_e32 v61, v0
	s_waitcnt vmcnt(9)
	v_mov_b32_e32 v62, v0
	v_mov_b32_e32 v63, v0
	v_mov_b32_e32 v64, v0
	v_mov_b32_e32 v65, v0
	s_waitcnt vmcnt(8)
	v_mov_b32_e32 v66, v0
	v_mov_b32_e32 v67, v0
	v_mov_b32_e32 v72, v0
	v_mov_b32_e32 v73, v0
	v_mov_b32_e32 v74, v0
	v_mov_b32_e32 v75, v0
	v_mov_b32_e32 v80, v0
	v_mov_b32_e32 v81, v0
	v_mov_b32_e32 v82, v0
	v_mov_b32_e32 v83, v0
	v_mov_b32_e32 v88, v0
	v_mov_b32_e32 v89, v0
	v_mov_b32_e32 v90, v0
	v_mov_b32_e32 v91, v0
	v_mov_b32_e32 v96, v0
	v_mov_b32_e32 v97, v0
	v_mov_b32_e32 v98, v0
	v_mov_b32_e32 v99, v0
	v_mov_b32_e32 v104, v0
	v_mov_b32_e32 v105, v0
	v_mov_b32_e32 v106, v0
	v_mov_b32_e32 v107, v0
	v_mov_b32_e32 v112, v0
	v_mov_b32_e32 v113, v0
	v_mov_b32_e32 v114, v0
	v_mov_b32_e32 v115, v0
	v_mov_b32_e32 v120, v0
	v_mov_b32_e32 v121, v0
	v_mov_b32_e32 v122, v0
	v_mov_b32_e32 v123, v0
	v_mov_b32_e32 v68, v0
	v_mov_b32_e32 v69, v0
	v_mov_b32_e32 v70, v0
	v_mov_b32_e32 v71, v0
	v_mov_b32_e32 v76, v0
	v_mov_b32_e32 v77, v0
	v_mov_b32_e32 v78, v0
	v_mov_b32_e32 v79, v0
	v_mov_b32_e32 v84, v0
	v_mov_b32_e32 v85, v0
	v_mov_b32_e32 v86, v0
	v_mov_b32_e32 v87, v0
	v_mov_b32_e32 v92, v0
	v_mov_b32_e32 v93, v0
	v_mov_b32_e32 v94, v0
	v_mov_b32_e32 v95, v0
	v_mov_b32_e32 v100, v0
	v_mov_b32_e32 v101, v0
	v_mov_b32_e32 v102, v0
	v_mov_b32_e32 v103, v0
	v_mov_b32_e32 v108, v0
	v_mov_b32_e32 v109, v0
	v_mov_b32_e32 v110, v0
	v_mov_b32_e32 v111, v0
	v_mov_b32_e32 v116, v0
	v_mov_b32_e32 v117, v0
	v_mov_b32_e32 v118, v0
	v_mov_b32_e32 v119, v0
	v_mov_b32_e32 v124, v0
	v_mov_b32_e32 v125, v0
	v_mov_b32_e32 v126, v0
	v_mov_b32_e32 v127, v0
	.p2align	6

; template <class Epi, class Sched, bool ALIGN_EPI = false, bool SP2 = false>
; __device__ __forceinline__ void gemm_phase(PG8_LAS unsigned char* lds, const Gemm g, const Sched& S, const Epi& E) {
;     ...
;         const char* nA = has_next ? (const char*)g.A + (size_t)nxt.pm * tstepA : cA; const char* nB = has_next ? (const char*)g.Bt + (size_t)nxt.pn * tstepB : cB;
;         for (int t = 0; t < nt; t += 2) {
;             const bool last = (t == nt - 2);
;     ...
;             const char* a1 = cA + PG8_KOFFA(t + 1);
;             const char* a2 = last ? nA : cA + PG8_KOFFA(t + 2); const char* b2 = last ? nB : cB + (size_t)(t + 2) * kstep;
;             const char* a3 = last ? nA + kstep : cA + PG8_KOFFA(t + 3); const char* b3 = b2 + kstep;
;     ...
; #pragma unroll
;         for (int a = 0; a < 2; ++a)
; #pragma unroll
;             for (int b = 0; b < 2; ++b)
; #pragma unroll
;                 for (int m = 0; m < 4; ++m)
; #pragma unroll
;                     for (int n = 0; n < 2; ++n) acc[a][b][m][n] = (f32x4){0.f, 0.f, 0.f, 0.f};
.LBB0_1008:
	s_ashr_i32 s27, s26, 31
	s_lshl_b64 s[0:1], s[26:27], 17
	s_add_u32 s28, s5, s0
	s_addc_u32 s29, s58, s1
	s_and_b64 s[0:1], s[6:7], exec
	s_cselect_b32 s0, s29, s39
	s_cselect_b32 s1, s28, s38
	s_ashr_i32 s25, s24, 31
	s_lshl_b64 s[30:31], s[24:25], 17
	s_add_u32 s30, s59, s30
	s_addc_u32 s31, s60, s31
	s_and_b64 s[40:41], s[6:7], exec
	s_cselect_b32 s25, s31, s37
	s_cselect_b32 s27, s30, s36
	s_add_u32 s85, s1, 0x80
	v_mov_b32_e32 v0, 0
	s_addc_u32 s90, s0, 0
	s_mov_b32 s44, 0
	s_mov_b64 s[40:41], -1
	s_mov_b64 s[42:43], 0
	v_mov_b32_e32 v1, v0
	v_mov_b32_e32 v2, v0
	v_mov_b32_e32 v3, v0
	v_mov_b32_e32 v4, v0
	v_mov_b32_e32 v5, v0
	v_mov_b32_e32 v6, v0
	v_mov_b32_e32 v7, v0
	v_mov_b32_e32 v12, v0
	v_mov_b32_e32 v13, v0
	v_mov_b32_e32 v14, v0
	v_mov_b32_e32 v15, v0
	v_mov_b32_e32 v20, v0
	v_mov_b32_e32 v21, v0
	v_mov_b32_e32 v22, v0
	v_mov_b32_e32 v23, v0
	v_mov_b32_e32 v28, v0
	v_mov_b32_e32 v29, v0
	v_mov_b32_e32 v30, v0
	v_mov_b32_e32 v31, v0
	v_mov_b32_e32 v36, v0
	v_mov_b32_e32 v37, v0
	v_mov_b32_e32 v38, v0
	v_mov_b32_e32 v39, v0
	v_mov_b32_e32 v44, v0
	v_mov_b32_e32 v45, v0
	v_mov_b32_e32 v46, v0
	v_mov_b32_e32 v47, v0
	v_mov_b32_e32 v52, v0
	v_mov_b32_e32 v53, v0
	v_mov_b32_e32 v54, v0
	v_mov_b32_e32 v55, v0
	v_mov_b32_e32 v8, v0
	v_mov_b32_e32 v9, v0
	v_mov_b32_e32 v10, v0
	v_mov_b32_e32 v11, v0
	v_mov_b32_e32 v16, v0
	v_mov_b32_e32 v17, v0
	v_mov_b32_e32 v18, v0
	v_mov_b32_e32 v19, v0
	v_mov_b32_e32 v24, v0
	v_mov_b32_e32 v25, v0
	v_mov_b32_e32 v26, v0
	v_mov_b32_e32 v27, v0
	v_mov_b32_e32 v32, v0
	v_mov_b32_e32 v33, v0
	v_mov_b32_e32 v34, v0
	v_mov_b32_e32 v35, v0
	v_mov_b32_e32 v40, v0
	v_mov_b32_e32 v41, v0
	v_mov_b32_e32 v42, v0
	v_mov_b32_e32 v43, v0
	v_mov_b32_e32 v48, v0
	v_mov_b32_e32 v49, v0
	v_mov_b32_e32 v50, v0
	v_mov_b32_e32 v51, v0
	v_mov_b32_e32 v56, v0
	v_mov_b32_e32 v57, v0
	v_mov_b32_e32 v58, v0
	v_mov_b32_e32 v59, v0
	v_mov_b32_e32 v60, v0
	v_mov_b32_e32 v61, v0
	v_mov_b32_e32 v62, v0
	v_mov_b32_e32 v63, v0
	v_mov_b32_e32 v64, v0
	v_mov_b32_e32 v65, v0
	v_mov_b32_e32 v66, v0
	v_mov_b32_e32 v67, v0
	v_mov_b32_e32 v68, v0
	v_mov_b32_e32 v69, v0
	v_mov_b32_e32 v70, v0
	v_mov_b32_e32 v71, v0
	v_mov_b32_e32 v76, v0
	v_mov_b32_e32 v77, v0
	v_mov_b32_e32 v78, v0
	v_mov_b32_e32 v79, v0
	v_mov_b32_e32 v84, v0
	v_mov_b32_e32 v85, v0
	v_mov_b32_e32 v86, v0
	v_mov_b32_e32 v87, v0
	v_mov_b32_e32 v92, v0
	v_mov_b32_e32 v93, v0
	v_mov_b32_e32 v94, v0
	v_mov_b32_e32 v95, v0
	v_mov_b32_e32 v100, v0
	v_mov_b32_e32 v101, v0
	v_mov_b32_e32 v102, v0
	v_mov_b32_e32 v103, v0
	v_mov_b32_e32 v108, v0
	v_mov_b32_e32 v109, v0
	v_mov_b32_e32 v110, v0
	v_mov_b32_e32 v111, v0
	v_mov_b32_e32 v116, v0
	v_mov_b32_e32 v117, v0
	v_mov_b32_e32 v118, v0
	v_mov_b32_e32 v119, v0
	v_mov_b32_e32 v72, v0
	v_mov_b32_e32 v73, v0
	v_mov_b32_e32 v74, v0
	v_mov_b32_e32 v75, v0
	v_mov_b32_e32 v80, v0
	v_mov_b32_e32 v81, v0
	v_mov_b32_e32 v82, v0
	v_mov_b32_e32 v83, v0
	v_mov_b32_e32 v88, v0
	v_mov_b32_e32 v89, v0
	v_mov_b32_e32 v90, v0
	v_mov_b32_e32 v91, v0
	v_mov_b32_e32 v96, v0
	v_mov_b32_e32 v97, v0
	v_mov_b32_e32 v98, v0
	v_mov_b32_e32 v99, v0
	v_mov_b32_e32 v104, v0
	v_mov_b32_e32 v105, v0
	v_mov_b32_e32 v106, v0
	v_mov_b32_e32 v107, v0
	v_mov_b32_e32 v112, v0
	v_mov_b32_e32 v113, v0
	v_mov_b32_e32 v114, v0
	v_mov_b32_e32 v115, v0
	v_mov_b32_e32 v120, v0
	v_mov_b32_e32 v121, v0
	v_mov_b32_e32 v122, v0
	v_mov_b32_e32 v123, v0
	v_mov_b32_e32 v124, v0
	v_mov_b32_e32 v125, v0
	v_mov_b32_e32 v126, v0
	v_mov_b32_e32 v127, v0
	.p2align	6

; template <class Epi, class Sched, bool ALIGN_EPI = false, bool SP2 = false>
; __device__ __forceinline__ void gemm_phase(PG8_LAS unsigned char* lds, const Gemm g, const Sched& S, const Epi& E) {
;     ...
;             const char* a1 = cA + PG8_KOFFA(t + 1);
;             const char* a2 = last ? nA : cA + PG8_KOFFA(t + 2); const char* b2 = last ? nB : cB + (size_t)(t + 2) * kstep;
;             const char* a3 = last ? nA + kstep : cA + PG8_KOFFA(t + 3); const char* b3 = b2 + kstep;
;     ...
; #pragma unroll
;         for (int a = 0; a < 2; ++a)
; #pragma unroll
;             for (int b = 0; b < 2; ++b)
; #pragma unroll
;                 for (int m = 0; m < 4; ++m)
; #pragma unroll
;                     for (int n = 0; n < 2; ++n) acc[a][b][m][n] = (f32x4){0.f, 0.f, 0.f, 0.f};
.LBB0_1113:
	s_add_u32 s28, s34, 0x8080
	s_addc_u32 s29, s35, 0
	s_add_u32 s0, s34, 0x10000
	s_addc_u32 s1, s35, 0
	s_add_u32 s64, s30, 0x100
	v_mov_b32_e32 v0, 0
	s_addc_u32 s65, s31, 0
	s_mov_b32 s66, -2
	s_waitcnt lgkmcnt(0)
	v_mov_b32_e32 v1, v0
	v_mov_b32_e32 v2, v0
	v_mov_b32_e32 v3, v0
	v_mov_b32_e32 v4, v0
	v_mov_b32_e32 v5, v0
	v_mov_b32_e32 v6, v0
	v_mov_b32_e32 v7, v0
	s_waitcnt vmcnt(21)
	v_mov_b32_e32 v16, v0
	v_mov_b32_e32 v17, v0
	s_waitcnt vmcnt(20)
	v_mov_b32_e32 v18, v0
	v_mov_b32_e32 v19, v0
	v_mov_b32_e32 v20, v0
	v_mov_b32_e32 v21, v0
	s_waitcnt vmcnt(19)
	v_mov_b32_e32 v22, v0
	v_mov_b32_e32 v23, v0
	s_waitcnt vmcnt(17)
	v_mov_b32_e32 v32, v0
	v_mov_b32_e32 v33, v0
	s_waitcnt vmcnt(16)
	v_mov_b32_e32 v34, v0
	v_mov_b32_e32 v35, v0
	v_mov_b32_e32 v36, v0
	v_mov_b32_e32 v37, v0
	s_waitcnt vmcnt(15)
	v_mov_b32_e32 v38, v0
	v_mov_b32_e32 v39, v0
	s_waitcnt vmcnt(13)
	v_mov_b32_e32 v48, v0
	v_mov_b32_e32 v49, v0
	s_waitcnt vmcnt(12)
	v_mov_b32_e32 v50, v0
	v_mov_b32_e32 v51, v0
	v_mov_b32_e32 v52, v0
	v_mov_b32_e32 v53, v0
	s_waitcnt vmcnt(11)
	v_mov_b32_e32 v54, v0
	v_mov_b32_e32 v55, v0
	v_mov_b32_e32 v8, v0
	v_mov_b32_e32 v9, v0
	v_mov_b32_e32 v10, v0
	v_mov_b32_e32 v11, v0
	v_mov_b32_e32 v12, v0
	v_mov_b32_e32 v13, v0
	v_mov_b32_e32 v14, v0
	v_mov_b32_e32 v15, v0
	v_mov_b32_e32 v24, v0
	v_mov_b32_e32 v25, v0
	v_mov_b32_e32 v26, v0
	v_mov_b32_e32 v27, v0
	v_mov_b32_e32 v28, v0
	v_mov_b32_e32 v29, v0
	v_mov_b32_e32 v30, v0
	v_mov_b32_e32 v31, v0
	v_mov_b32_e32 v40, v0
	v_mov_b32_e32 v41, v0
	v_mov_b32_e32 v42, v0
	v_mov_b32_e32 v43, v0
	v_mov_b32_e32 v44, v0
	v_mov_b32_e32 v45, v0
	v_mov_b32_e32 v46, v0
	v_mov_b32_e32 v47, v0
	v_mov_b32_e32 v56, v0
	v_mov_b32_e32 v57, v0
	s_waitcnt vmcnt(10)
	v_mov_b32_e32 v58, v0
	v_mov_b32_e32 v59, v0
	v_mov_b32_e32 v60, v0
	v_mov_b32_e32 v61, v0
	s_waitcnt vmcnt(9)
	v_mov_b32_e32 v62, v0
	v_mov_b32_e32 v63, v0
	v_mov_b32_e32 v64, v0
	v_mov_b32_e32 v65, v0
	s_waitcnt vmcnt(8)
	v_mov_b32_e32 v66, v0
	v_mov_b32_e32 v67, v0
	v_mov_b32_e32 v68, v0
	v_mov_b32_e32 v69, v0
	v_mov_b32_e32 v70, v0
	v_mov_b32_e32 v71, v0
	v_mov_b32_e32 v80, v0
	v_mov_b32_e32 v81, v0
	v_mov_b32_e32 v82, v0
	v_mov_b32_e32 v83, v0
	v_mov_b32_e32 v84, v0
	v_mov_b32_e32 v85, v0
	v_mov_b32_e32 v86, v0
	v_mov_b32_e32 v87, v0
	v_mov_b32_e32 v96, v0
	v_mov_b32_e32 v97, v0
	v_mov_b32_e32 v98, v0
	v_mov_b32_e32 v99, v0
	v_mov_b32_e32 v100, v0
	v_mov_b32_e32 v101, v0
	v_mov_b32_e32 v102, v0
	v_mov_b32_e32 v103, v0
	v_mov_b32_e32 v120, v0
	v_mov_b32_e32 v121, v0
	v_mov_b32_e32 v122, v0
	v_mov_b32_e32 v123, v0
	v_mov_b32_e32 v128, v0
	v_mov_b32_e32 v129, v0
	v_mov_b32_e32 v130, v0
	v_mov_b32_e32 v131, v0
	v_mov_b32_e32 v72, v0
	v_mov_b32_e32 v73, v0
	v_mov_b32_e32 v74, v0
	v_mov_b32_e32 v75, v0
	v_mov_b32_e32 v76, v0
	v_mov_b32_e32 v77, v0
	v_mov_b32_e32 v78, v0
	v_mov_b32_e32 v79, v0
	v_mov_b32_e32 v88, v0
	v_mov_b32_e32 v89, v0
	v_mov_b32_e32 v90, v0
	v_mov_b32_e32 v91, v0
	v_mov_b32_e32 v92, v0
	v_mov_b32_e32 v93, v0
	v_mov_b32_e32 v94, v0
	v_mov_b32_e32 v95, v0
	v_mov_b32_e32 v112, v0
	v_mov_b32_e32 v113, v0
	v_mov_b32_e32 v114, v0
	v_mov_b32_e32 v115, v0
	v_mov_b32_e32 v116, v0
	v_mov_b32_e32 v117, v0
	v_mov_b32_e32 v118, v0
	v_mov_b32_e32 v119, v0
	v_mov_b32_e32 v132, v0
	v_mov_b32_e32 v133, v0
	v_mov_b32_e32 v134, v0
	v_mov_b32_e32 v135, v0
	v_mov_b32_e32 v136, v0
	v_mov_b32_e32 v137, v0
	v_mov_b32_e32 v138, v0
	v_mov_b32_e32 v139, v0
	.p2align	6

; template <class Epi, class Sched, bool ALIGN_EPI = false, bool SP2 = false>
; __device__ __forceinline__ void gemm_phase(PG8_LAS unsigned char* lds, const Gemm g, const Sched& S, const Epi& E) {
;     ...
;         const char* nA = has_next ? (const char*)g.A + (size_t)nxt.pm * tstepA : cA; const char* nB = has_next ? (const char*)g.Bt + (size_t)nxt.pn * tstepB : cB;
;         for (int t = 0; t < nt; t += 2) {
;             const bool last = (t == nt - 2);
;     ...
;             const char* a1 = cA + PG8_KOFFA(t + 1);
;             const char* a2 = last ? nA : cA + PG8_KOFFA(t + 2); const char* b2 = last ? nB : cB + (size_t)(t + 2) * kstep;
;             const char* a3 = last ? nA + kstep : cA + PG8_KOFFA(t + 3); const char* b3 = b2 + kstep;
;     ...
; #pragma unroll
;         for (int a = 0; a < 2; ++a)
; #pragma unroll
;             for (int b = 0; b < 2; ++b)
; #pragma unroll
;                 for (int m = 0; m < 4; ++m)
; #pragma unroll
;                     for (int n = 0; n < 2; ++n) acc[a][b][m][n] = (f32x4){0.f, 0.f, 0.f, 0.f};
.LBB0_1234:
	s_ashr_i32 s35, s34, 31
	s_lshl_b64 s[0:1], s[34:35], 20
	s_add_u32 s36, s16, s0
	s_addc_u32 s37, s17, s1
	s_and_b64 s[0:1], s[8:9], exec
	s_cselect_b32 s0, s37, s11
	s_cselect_b32 s1, s36, s10
	s_ashr_i32 s31, s30, 31
	s_lshl_b64 s[4:5], s[30:31], 20
	s_add_u32 s38, s51, s4
	s_addc_u32 s39, s52, s5
	s_and_b64 s[4:5], s[8:9], exec
	s_cselect_b32 s4, s39, s43
	s_cselect_b32 s5, s38, s42
	s_add_u32 s31, s1, 0x80
	s_addc_u32 s35, s0, 0
	s_add_u32 s41, s42, 0x100
	v_mov_b32_e32 v0, 0
	s_addc_u32 s73, s43, 0
	s_mov_b32 s76, -2
	s_mov_b32 s77, 0x18000
	s_mov_b64 s[42:43], 0
	s_waitcnt lgkmcnt(0)
	v_mov_b32_e32 v1, v0
	v_mov_b32_e32 v2, v0
	v_mov_b32_e32 v3, v0
	v_mov_b32_e32 v4, v0
	v_mov_b32_e32 v5, v0
	v_mov_b32_e32 v6, v0
	v_mov_b32_e32 v7, v0
	s_waitcnt vmcnt(21)
	v_mov_b32_e32 v16, v0
	v_mov_b32_e32 v17, v0
	s_waitcnt vmcnt(20)
	v_mov_b32_e32 v18, v0
	v_mov_b32_e32 v19, v0
	v_mov_b32_e32 v20, v0
	v_mov_b32_e32 v21, v0
	s_waitcnt vmcnt(19)
	v_mov_b32_e32 v22, v0
	v_mov_b32_e32 v23, v0
	s_waitcnt vmcnt(17)
	v_mov_b32_e32 v32, v0
	v_mov_b32_e32 v33, v0
	s_waitcnt vmcnt(16)
	v_mov_b32_e32 v34, v0
	v_mov_b32_e32 v35, v0
	v_mov_b32_e32 v36, v0
	v_mov_b32_e32 v37, v0
	s_waitcnt vmcnt(15)
	v_mov_b32_e32 v38, v0
	v_mov_b32_e32 v39, v0
	s_waitcnt vmcnt(13)
	v_mov_b32_e32 v48, v0
	v_mov_b32_e32 v49, v0
	s_waitcnt vmcnt(12)
	v_mov_b32_e32 v50, v0
	v_mov_b32_e32 v51, v0
	v_mov_b32_e32 v52, v0
	v_mov_b32_e32 v53, v0
	s_waitcnt vmcnt(11)
	v_mov_b32_e32 v54, v0
	v_mov_b32_e32 v55, v0
	v_mov_b32_e32 v8, v0
	v_mov_b32_e32 v9, v0
	v_mov_b32_e32 v10, v0
	v_mov_b32_e32 v11, v0
	v_mov_b32_e32 v12, v0
	v_mov_b32_e32 v13, v0
	v_mov_b32_e32 v14, v0
	v_mov_b32_e32 v15, v0
	v_mov_b32_e32 v24, v0
	v_mov_b32_e32 v25, v0
	v_mov_b32_e32 v26, v0
	v_mov_b32_e32 v27, v0
	v_mov_b32_e32 v28, v0
	v_mov_b32_e32 v29, v0
	v_mov_b32_e32 v30, v0
	v_mov_b32_e32 v31, v0
	v_mov_b32_e32 v40, v0
	v_mov_b32_e32 v41, v0
	v_mov_b32_e32 v42, v0
	v_mov_b32_e32 v43, v0
	v_mov_b32_e32 v44, v0
	v_mov_b32_e32 v45, v0
	v_mov_b32_e32 v46, v0
	v_mov_b32_e32 v47, v0
	v_mov_b32_e32 v56, v0
	v_mov_b32_e32 v57, v0
	s_waitcnt vmcnt(10)
	v_mov_b32_e32 v58, v0
	v_mov_b32_e32 v59, v0
	v_mov_b32_e32 v60, v0
	v_mov_b32_e32 v61, v0
	s_waitcnt vmcnt(9)
	v_mov_b32_e32 v62, v0
	v_mov_b32_e32 v63, v0
	v_mov_b32_e32 v64, v0
	v_mov_b32_e32 v65, v0
	s_waitcnt vmcnt(8)
	v_mov_b32_e32 v66, v0
	v_mov_b32_e32 v67, v0
	v_mov_b32_e32 v68, v0
	v_mov_b32_e32 v69, v0
	v_mov_b32_e32 v70, v0
	v_mov_b32_e32 v71, v0
	v_mov_b32_e32 v80, v0
	v_mov_b32_e32 v81, v0
	v_mov_b32_e32 v82, v0
	v_mov_b32_e32 v83, v0
	v_mov_b32_e32 v84, v0
	v_mov_b32_e32 v85, v0
	v_mov_b32_e32 v86, v0
	v_mov_b32_e32 v87, v0
	v_mov_b32_e32 v96, v0
	v_mov_b32_e32 v97, v0
	v_mov_b32_e32 v98, v0
	v_mov_b32_e32 v99, v0
	v_mov_b32_e32 v100, v0
	v_mov_b32_e32 v101, v0
	v_mov_b32_e32 v102, v0
	v_mov_b32_e32 v103, v0
	v_mov_b32_e32 v112, v0
	v_mov_b32_e32 v113, v0
	v_mov_b32_e32 v114, v0
	v_mov_b32_e32 v115, v0
	v_mov_b32_e32 v116, v0
	v_mov_b32_e32 v117, v0
	v_mov_b32_e32 v118, v0
	v_mov_b32_e32 v119, v0
	v_mov_b32_e32 v72, v0
	v_mov_b32_e32 v73, v0
	v_mov_b32_e32 v74, v0
	v_mov_b32_e32 v75, v0
	v_mov_b32_e32 v76, v0
	v_mov_b32_e32 v77, v0
	v_mov_b32_e32 v78, v0
	v_mov_b32_e32 v79, v0
	v_mov_b32_e32 v88, v0
	v_mov_b32_e32 v89, v0
	v_mov_b32_e32 v90, v0
	v_mov_b32_e32 v91, v0
	v_mov_b32_e32 v92, v0
	v_mov_b32_e32 v93, v0
	v_mov_b32_e32 v94, v0
	v_mov_b32_e32 v95, v0
	v_mov_b32_e32 v104, v0
	v_mov_b32_e32 v105, v0
	v_mov_b32_e32 v106, v0
	v_mov_b32_e32 v107, v0
	v_mov_b32_e32 v108, v0
	v_mov_b32_e32 v109, v0
	v_mov_b32_e32 v110, v0
	v_mov_b32_e32 v111, v0
	v_mov_b32_e32 v120, v0
	v_mov_b32_e32 v121, v0
	v_mov_b32_e32 v122, v0
	v_mov_b32_e32 v123, v0
	v_mov_b32_e32 v124, v0
	v_mov_b32_e32 v125, v0
	v_mov_b32_e32 v126, v0
	v_mov_b32_e32 v127, v0
	.p2align	6

; template <class Epi, class Sched, bool ALIGN_EPI = false, bool SP2 = false>
; __device__ __forceinline__ void gemm_phase(PG8_LAS unsigned char* lds, const Gemm g, const Sched& S, const Epi& E) {
;     ...
;         const char* nA = has_next ? (const char*)g.A + (size_t)nxt.pm * tstepA : cA; const char* nB = has_next ? (const char*)g.Bt + (size_t)nxt.pn * tstepB : cB;
;         for (int t = 0; t < nt; t += 2) {
;             const bool last = (t == nt - 2);
;     ...
;             const char* a1 = cA + PG8_KOFFA(t + 1);
;             const char* a2 = last ? nA : cA + PG8_KOFFA(t + 2); const char* b2 = last ? nB : cB + (size_t)(t + 2) * kstep;
;             const char* a3 = last ? nA + kstep : cA + PG8_KOFFA(t + 3); const char* b3 = b2 + kstep;
;     ...
; #pragma unroll
;         for (int a = 0; a < 2; ++a)
; #pragma unroll
;             for (int b = 0; b < 2; ++b)
; #pragma unroll
;                 for (int m = 0; m < 4; ++m)
; #pragma unroll
;                     for (int n = 0; n < 2; ++n) acc[a][b][m][n] = (f32x4){0.f, 0.f, 0.f, 0.f};
.LBB0_1379:
	s_ashr_i32 s23, s22, 31
	s_lshl_b64 s[0:1], s[22:23], 20
	s_add_u32 s24, s33, s0
	s_addc_u32 s25, s42, s1
	s_and_b64 s[0:1], s[6:7], exec
	s_cselect_b32 s0, s25, s9
	s_cselect_b32 s1, s24, s8
	s_ashr_i32 s21, s20, 31
	s_lshl_b64 s[26:27], s[20:21], 20
	s_add_u32 s26, s43, s26
	s_addc_u32 s27, s44, s27
	s_and_b64 s[36:37], s[6:7], exec
	s_cselect_b32 s21, s27, s35
	s_cselect_b32 s23, s26, s34
	s_add_u32 s29, s1, 0x80
	s_addc_u32 s67, s0, 0
	s_add_u32 s68, s34, 0x100
	v_mov_b32_e32 v0, 0
	s_addc_u32 s69, s35, 0
	s_mov_b32 s70, -2
	s_mov_b32 s71, 0x18000
	s_mov_b64 s[34:35], 0
	v_mov_b32_e32 v1, v0
	v_mov_b32_e32 v2, v0
	v_mov_b32_e32 v3, v0
	v_mov_b32_e32 v8, v0
	v_mov_b32_e32 v9, v0
	s_waitcnt vmcnt(22)
	v_mov_b32_e32 v10, v0
	v_mov_b32_e32 v11, v0
	s_waitcnt vmcnt(21)
	v_mov_b32_e32 v16, v0
	v_mov_b32_e32 v17, v0
	s_waitcnt vmcnt(20)
	v_mov_b32_e32 v18, v0
	v_mov_b32_e32 v19, v0
	s_waitcnt vmcnt(19)
	v_mov_b32_e32 v24, v0
	v_mov_b32_e32 v25, v0
	s_waitcnt vmcnt(18)
	v_mov_b32_e32 v26, v0
	v_mov_b32_e32 v27, v0
	s_waitcnt vmcnt(17)
	v_mov_b32_e32 v32, v0
	v_mov_b32_e32 v33, v0
	s_waitcnt vmcnt(16)
	v_mov_b32_e32 v34, v0
	v_mov_b32_e32 v35, v0
	s_waitcnt vmcnt(15)
	v_mov_b32_e32 v40, v0
	v_mov_b32_e32 v41, v0
	s_waitcnt vmcnt(14)
	v_mov_b32_e32 v42, v0
	v_mov_b32_e32 v43, v0
	s_waitcnt vmcnt(13)
	v_mov_b32_e32 v48, v0
	v_mov_b32_e32 v49, v0
	s_waitcnt vmcnt(12)
	v_mov_b32_e32 v50, v0
	v_mov_b32_e32 v51, v0
	s_waitcnt vmcnt(11)
	v_mov_b32_e32 v56, v0
	v_mov_b32_e32 v57, v0
	s_waitcnt vmcnt(10)
	v_mov_b32_e32 v58, v0
	v_mov_b32_e32 v59, v0
	v_mov_b32_e32 v4, v0
	v_mov_b32_e32 v5, v0
	v_mov_b32_e32 v6, v0
	v_mov_b32_e32 v7, v0
	v_mov_b32_e32 v12, v0
	v_mov_b32_e32 v13, v0
	v_mov_b32_e32 v14, v0
	v_mov_b32_e32 v15, v0
	v_mov_b32_e32 v20, v0
	v_mov_b32_e32 v21, v0
	v_mov_b32_e32 v22, v0
	v_mov_b32_e32 v23, v0
	v_mov_b32_e32 v28, v0
	v_mov_b32_e32 v29, v0
	v_mov_b32_e32 v30, v0
	v_mov_b32_e32 v31, v0
	v_mov_b32_e32 v36, v0
	v_mov_b32_e32 v37, v0
	v_mov_b32_e32 v38, v0
	v_mov_b32_e32 v39, v0
	v_mov_b32_e32 v44, v0
	v_mov_b32_e32 v45, v0
	v_mov_b32_e32 v46, v0
	v_mov_b32_e32 v47, v0
	v_mov_b32_e32 v52, v0
	v_mov_b32_e32 v53, v0
	v_mov_b32_e32 v54, v0
	v_mov_b32_e32 v55, v0
	v_mov_b32_e32 v60, v0
	v_mov_b32_e32 v61, v0
	s_waitcnt vmcnt(9)
	v_mov_b32_e32 v62, v0
	v_mov_b32_e32 v63, v0
	v_mov_b32_e32 v64, v0
	v_mov_b32_e32 v65, v0
	s_waitcnt vmcnt(8)
	v_mov_b32_e32 v66, v0
	v_mov_b32_e32 v67, v0
	v_mov_b32_e32 v72, v0
	v_mov_b32_e32 v73, v0
	v_mov_b32_e32 v74, v0
	v_mov_b32_e32 v75, v0
	v_mov_b32_e32 v80, v0
	v_mov_b32_e32 v81, v0
	v_mov_b32_e32 v82, v0
	v_mov_b32_e32 v83, v0
	v_mov_b32_e32 v88, v0
	v_mov_b32_e32 v89, v0
	v_mov_b32_e32 v90, v0
	v_mov_b32_e32 v91, v0
	v_mov_b32_e32 v96, v0
	v_mov_b32_e32 v97, v0
	v_mov_b32_e32 v98, v0
	v_mov_b32_e32 v99, v0
	v_mov_b32_e32 v104, v0
	v_mov_b32_e32 v105, v0
	v_mov_b32_e32 v106, v0
	v_mov_b32_e32 v107, v0
	v_mov_b32_e32 v112, v0
	v_mov_b32_e32 v113, v0
	v_mov_b32_e32 v114, v0
	v_mov_b32_e32 v115, v0
	v_mov_b32_e32 v120, v0
	v_mov_b32_e32 v121, v0
	v_mov_b32_e32 v122, v0
	v_mov_b32_e32 v123, v0
	v_mov_b32_e32 v68, v0
	v_mov_b32_e32 v69, v0
	v_mov_b32_e32 v70, v0
	v_mov_b32_e32 v71, v0
	v_mov_b32_e32 v76, v0
	v_mov_b32_e32 v77, v0
	v_mov_b32_e32 v78, v0
	v_mov_b32_e32 v79, v0
	v_mov_b32_e32 v84, v0
	v_mov_b32_e32 v85, v0
	v_mov_b32_e32 v86, v0
	v_mov_b32_e32 v87, v0
	v_mov_b32_e32 v92, v0
	v_mov_b32_e32 v93, v0
	v_mov_b32_e32 v94, v0
	v_mov_b32_e32 v95, v0
	v_mov_b32_e32 v100, v0
	v_mov_b32_e32 v101, v0
	v_mov_b32_e32 v102, v0
	v_mov_b32_e32 v103, v0
	v_mov_b32_e32 v108, v0
	v_mov_b32_e32 v109, v0
	v_mov_b32_e32 v110, v0
	v_mov_b32_e32 v111, v0
	v_mov_b32_e32 v116, v0
	v_mov_b32_e32 v117, v0
	v_mov_b32_e32 v118, v0
	v_mov_b32_e32 v119, v0
	v_mov_b32_e32 v124, v0
	v_mov_b32_e32 v125, v0
	v_mov_b32_e32 v126, v0
	v_mov_b32_e32 v127, v0
	.p2align	6

; template <class Epi, class Sched, bool ALIGN_EPI = false, bool SP2 = false>
; __device__ __forceinline__ void gemm_phase(PG8_LAS unsigned char* lds, const Gemm g, const Sched& S, const Epi& E) {
;     ...
;         const char* nA = has_next ? (const char*)g.A + (size_t)nxt.pm * tstepA : cA; const char* nB = has_next ? (const char*)g.Bt + (size_t)nxt.pn * tstepB : cB;
;         for (int t = 0; t < nt; t += 2) {
;             const bool last = (t == nt - 2);
;     ...
;             const char* a1 = cA + PG8_KOFFA(t + 1);
;             const char* a2 = last ? nA : cA + PG8_KOFFA(t + 2); const char* b2 = last ? nB : cB + (size_t)(t + 2) * kstep;
;             const char* a3 = last ? nA + kstep : cA + PG8_KOFFA(t + 3); const char* b3 = b2 + kstep;
;     ...
; #pragma unroll
;         for (int a = 0; a < 2; ++a)
; #pragma unroll
;             for (int b = 0; b < 2; ++b)
; #pragma unroll
;                 for (int m = 0; m < 4; ++m)
; #pragma unroll
;                     for (int n = 0; n < 2; ++n) acc[a][b][m][n] = (f32x4){0.f, 0.f, 0.f, 0.f};
.LBB0_1629:
	s_ashr_i32 s31, s30, 31
	s_lshl_b64 s[0:1], s[30:31], 20
	s_add_u32 s34, s33, s0
	s_addc_u32 s35, s52, s1
	s_and_b64 s[0:1], s[6:7], exec
	s_cselect_b32 s0, s35, s43
	s_cselect_b32 s1, s34, s42
	s_ashr_i32 s29, s28, 31
	s_lshl_b64 s[36:37], s[28:29], 20
	s_add_u32 s36, s53, s36
	s_addc_u32 s37, s54, s37
	s_and_b64 s[44:45], s[6:7], exec
	s_cselect_b32 s9, s37, s41
	s_cselect_b32 s29, s36, s40
	s_add_u32 s31, s1, 0x80
	v_mov_b32_e32 v0, 0
	s_addc_u32 s77, s0, 0
	s_mov_b32 s46, -2
	s_mov_b64 s[44:45], 0x100
	v_mov_b32_e32 v1, v0
	v_mov_b32_e32 v2, v0
	v_mov_b32_e32 v3, v0
	v_mov_b32_e32 v4, v0
	v_mov_b32_e32 v5, v0
	v_mov_b32_e32 v6, v0
	v_mov_b32_e32 v7, v0
	s_waitcnt vmcnt(22)
	v_mov_b32_e32 v12, v0
	v_mov_b32_e32 v13, v0
	s_waitcnt vmcnt(21)
	v_mov_b32_e32 v14, v0
	v_mov_b32_e32 v15, v0
	s_waitcnt vmcnt(20)
	v_mov_b32_e32 v20, v0
	v_mov_b32_e32 v21, v0
	s_waitcnt vmcnt(19)
	v_mov_b32_e32 v22, v0
	v_mov_b32_e32 v23, v0
	s_waitcnt vmcnt(18)
	v_mov_b32_e32 v28, v0
	v_mov_b32_e32 v29, v0
	s_waitcnt vmcnt(17)
	v_mov_b32_e32 v30, v0
	v_mov_b32_e32 v31, v0
	s_waitcnt vmcnt(16)
	v_mov_b32_e32 v36, v0
	v_mov_b32_e32 v37, v0
	s_waitcnt vmcnt(15)
	v_mov_b32_e32 v38, v0
	v_mov_b32_e32 v39, v0
	s_waitcnt vmcnt(14)
	v_mov_b32_e32 v44, v0
	v_mov_b32_e32 v45, v0
	s_waitcnt vmcnt(13)
	v_mov_b32_e32 v46, v0
	v_mov_b32_e32 v47, v0
	s_waitcnt vmcnt(12)
	v_mov_b32_e32 v52, v0
	v_mov_b32_e32 v53, v0
	s_waitcnt vmcnt(11)
	v_mov_b32_e32 v54, v0
	v_mov_b32_e32 v55, v0
	v_mov_b32_e32 v8, v0
	v_mov_b32_e32 v9, v0
	v_mov_b32_e32 v10, v0
	v_mov_b32_e32 v11, v0
	v_mov_b32_e32 v16, v0
	v_mov_b32_e32 v17, v0
	v_mov_b32_e32 v18, v0
	v_mov_b32_e32 v19, v0
	v_mov_b32_e32 v24, v0
	v_mov_b32_e32 v25, v0
	v_mov_b32_e32 v26, v0
	v_mov_b32_e32 v27, v0
	v_mov_b32_e32 v32, v0
	v_mov_b32_e32 v33, v0
	v_mov_b32_e32 v34, v0
	v_mov_b32_e32 v35, v0
	v_mov_b32_e32 v40, v0
	v_mov_b32_e32 v41, v0
	v_mov_b32_e32 v42, v0
	v_mov_b32_e32 v43, v0
	v_mov_b32_e32 v48, v0
	v_mov_b32_e32 v49, v0
	v_mov_b32_e32 v50, v0
	v_mov_b32_e32 v51, v0
	v_mov_b32_e32 v56, v0
	v_mov_b32_e32 v57, v0
	s_waitcnt vmcnt(10)
	v_mov_b32_e32 v58, v0
	v_mov_b32_e32 v59, v0
	v_mov_b32_e32 v60, v0
	v_mov_b32_e32 v61, v0
	s_waitcnt vmcnt(9)
	v_mov_b32_e32 v62, v0
	v_mov_b32_e32 v63, v0
	v_mov_b32_e32 v64, v0
	v_mov_b32_e32 v65, v0
	s_waitcnt vmcnt(8)
	v_mov_b32_e32 v66, v0
	v_mov_b32_e32 v67, v0
	v_mov_b32_e32 v68, v0
	v_mov_b32_e32 v69, v0
	v_mov_b32_e32 v70, v0
	v_mov_b32_e32 v71, v0
	v_mov_b32_e32 v76, v0
	v_mov_b32_e32 v77, v0
	v_mov_b32_e32 v78, v0
	v_mov_b32_e32 v79, v0
	v_mov_b32_e32 v84, v0
	v_mov_b32_e32 v85, v0
	v_mov_b32_e32 v86, v0
	v_mov_b32_e32 v87, v0
	v_mov_b32_e32 v92, v0
	v_mov_b32_e32 v93, v0
	v_mov_b32_e32 v94, v0
	v_mov_b32_e32 v95, v0
	v_mov_b32_e32 v100, v0
	v_mov_b32_e32 v101, v0
	v_mov_b32_e32 v102, v0
	v_mov_b32_e32 v103, v0
	v_mov_b32_e32 v108, v0
	v_mov_b32_e32 v109, v0
	v_mov_b32_e32 v110, v0
	v_mov_b32_e32 v111, v0
	v_mov_b32_e32 v116, v0
	v_mov_b32_e32 v117, v0
	v_mov_b32_e32 v118, v0
	v_mov_b32_e32 v119, v0
	v_mov_b32_e32 v72, v0
	v_mov_b32_e32 v73, v0
	v_mov_b32_e32 v74, v0
	v_mov_b32_e32 v75, v0
	v_mov_b32_e32 v80, v0
	v_mov_b32_e32 v81, v0
	v_mov_b32_e32 v82, v0
	v_mov_b32_e32 v83, v0
	v_mov_b32_e32 v88, v0
	v_mov_b32_e32 v89, v0
	v_mov_b32_e32 v90, v0
	v_mov_b32_e32 v91, v0
	v_mov_b32_e32 v96, v0
	v_mov_b32_e32 v97, v0
	v_mov_b32_e32 v98, v0
	v_mov_b32_e32 v99, v0
	v_mov_b32_e32 v104, v0
	v_mov_b32_e32 v105, v0
	v_mov_b32_e32 v106, v0
	v_mov_b32_e32 v107, v0
	v_mov_b32_e32 v112, v0
	v_mov_b32_e32 v113, v0
	v_mov_b32_e32 v114, v0
	v_mov_b32_e32 v115, v0
	v_mov_b32_e32 v120, v0
	v_mov_b32_e32 v121, v0
	v_mov_b32_e32 v122, v0
	v_mov_b32_e32 v123, v0
	v_mov_b32_e32 v124, v0
	v_mov_b32_e32 v125, v0
	v_mov_b32_e32 v126, v0
	v_mov_b32_e32 v127, v0
	.p2align	6

; template <class Epi, class Sched, bool ALIGN_EPI = false, bool SP2 = false>
; __device__ __forceinline__ void gemm_phase(PG8_LAS unsigned char* lds, const Gemm g, const Sched& S, const Epi& E) {
;     ...
;         const char* nA = has_next ? (const char*)g.A + (size_t)nxt.pm * tstepA : cA; const char* nB = has_next ? (const char*)g.Bt + (size_t)nxt.pn * tstepB : cB;
;         for (int t = 0; t < nt; t += 2) {
;             const bool last = (t == nt - 2);
;     ...
;             const char* a1 = cA + PG8_KOFFA(t + 1);
;             const char* a2 = last ? nA : cA + PG8_KOFFA(t + 2); const char* b2 = last ? nB : cB + (size_t)(t + 2) * kstep;
;             const char* a3 = last ? nA + kstep : cA + PG8_KOFFA(t + 3); const char* b3 = b2 + kstep;
;     ...
; #pragma unroll
;         for (int a = 0; a < 2; ++a)
; #pragma unroll
;             for (int b = 0; b < 2; ++b)
; #pragma unroll
;                 for (int m = 0; m < 4; ++m)
; #pragma unroll
;                     for (int n = 0; n < 2; ++n) acc[a][b][m][n] = (f32x4){0.f, 0.f, 0.f, 0.f};
.LBB0_1824:
	s_ashr_i32 s35, s34, 31
	s_lshl_b64 s[0:1], s[34:35], 20
	s_add_u32 s36, s5, s0
	s_addc_u32 s37, s33, s1
	s_and_b64 s[0:1], s[8:9], exec
	s_cselect_b32 s0, s37, s45
	s_cselect_b32 s1, s36, s44
	s_ashr_i32 s31, s30, 31
	s_lshl_b64 s[38:39], s[30:31], 20
	s_add_u32 s38, s50, s38
	s_addc_u32 s39, s51, s39
	s_and_b64 s[46:47], s[8:9], exec
	s_cselect_b32 s16, s39, s11
	s_cselect_b32 s31, s38, s10
	s_add_u32 s46, s44, 0x80000
	s_addc_u32 s47, s45, 0
	s_add_u32 s35, s1, 0x80
	s_addc_u32 s70, s0, 0
	s_add_u32 s71, s44, 0x180
	s_addc_u32 s72, s45, 0
	s_add_u32 s73, s10, 0x100
	s_addc_u32 s76, s11, 0
	s_add_u32 s77, s44, 0x100
	s_addc_u32 s78, s45, 0
	s_add_u32 s10, s46, 0x80
	v_mov_b32_e32 v0, 0
	s_addc_u32 s11, s47, 0
	s_mov_b32 s79, -2
	s_waitcnt lgkmcnt(0)
	v_mov_b32_e32 v1, v0
	v_mov_b32_e32 v2, v0
	v_mov_b32_e32 v3, v0
	v_mov_b32_e32 v4, v0
	v_mov_b32_e32 v5, v0
	s_waitcnt vmcnt(23)
	v_mov_b32_e32 v6, v0
	v_mov_b32_e32 v7, v0
	s_waitcnt vmcnt(21)
	v_mov_b32_e32 v16, v0
	v_mov_b32_e32 v17, v0
	s_waitcnt vmcnt(20)
	v_mov_b32_e32 v18, v0
	v_mov_b32_e32 v19, v0
	v_mov_b32_e32 v20, v0
	v_mov_b32_e32 v21, v0
	s_waitcnt vmcnt(19)
	v_mov_b32_e32 v22, v0
	v_mov_b32_e32 v23, v0
	s_waitcnt vmcnt(17)
	v_mov_b32_e32 v32, v0
	v_mov_b32_e32 v33, v0
	s_waitcnt vmcnt(16)
	v_mov_b32_e32 v34, v0
	v_mov_b32_e32 v35, v0
	v_mov_b32_e32 v36, v0
	v_mov_b32_e32 v37, v0
	s_waitcnt vmcnt(15)
	v_mov_b32_e32 v38, v0
	v_mov_b32_e32 v39, v0
	s_waitcnt vmcnt(13)
	v_mov_b32_e32 v48, v0
	v_mov_b32_e32 v49, v0
	s_waitcnt vmcnt(12)
	v_mov_b32_e32 v50, v0
	v_mov_b32_e32 v51, v0
	v_mov_b32_e32 v52, v0
	v_mov_b32_e32 v53, v0
	s_waitcnt vmcnt(11)
	v_mov_b32_e32 v54, v0
	v_mov_b32_e32 v55, v0
	v_mov_b32_e32 v8, v0
	v_mov_b32_e32 v9, v0
	v_mov_b32_e32 v10, v0
	v_mov_b32_e32 v11, v0
	v_mov_b32_e32 v12, v0
	v_mov_b32_e32 v13, v0
	v_mov_b32_e32 v14, v0
	v_mov_b32_e32 v15, v0
	v_mov_b32_e32 v24, v0
	v_mov_b32_e32 v25, v0
	v_mov_b32_e32 v26, v0
	v_mov_b32_e32 v27, v0
	v_mov_b32_e32 v28, v0
	v_mov_b32_e32 v29, v0
	v_mov_b32_e32 v30, v0
	v_mov_b32_e32 v31, v0
	v_mov_b32_e32 v40, v0
	v_mov_b32_e32 v41, v0
	v_mov_b32_e32 v42, v0
	v_mov_b32_e32 v43, v0
	v_mov_b32_e32 v44, v0
	v_mov_b32_e32 v45, v0
	v_mov_b32_e32 v46, v0
	v_mov_b32_e32 v47, v0
	v_mov_b32_e32 v56, v0
	v_mov_b32_e32 v57, v0
	s_waitcnt vmcnt(10)
	v_mov_b32_e32 v58, v0
	v_mov_b32_e32 v59, v0
	v_mov_b32_e32 v60, v0
	v_mov_b32_e32 v61, v0
	s_waitcnt vmcnt(9)
	v_mov_b32_e32 v62, v0
	v_mov_b32_e32 v63, v0
	v_mov_b32_e32 v64, v0
	v_mov_b32_e32 v65, v0
	s_waitcnt vmcnt(8)
	v_mov_b32_e32 v66, v0
	v_mov_b32_e32 v67, v0
	v_mov_b32_e32 v68, v0
	v_mov_b32_e32 v69, v0
	v_mov_b32_e32 v70, v0
	v_mov_b32_e32 v71, v0
	v_mov_b32_e32 v80, v0
	v_mov_b32_e32 v81, v0
	v_mov_b32_e32 v82, v0
	v_mov_b32_e32 v83, v0
	v_mov_b32_e32 v84, v0
	v_mov_b32_e32 v85, v0
	v_mov_b32_e32 v86, v0
	v_mov_b32_e32 v87, v0
	v_mov_b32_e32 v112, v0
	v_mov_b32_e32 v113, v0
	v_mov_b32_e32 v114, v0
	v_mov_b32_e32 v115, v0
	v_mov_b32_e32 v116, v0
	v_mov_b32_e32 v117, v0
	v_mov_b32_e32 v118, v0
	v_mov_b32_e32 v119, v0
	v_mov_b32_e32 v132, v0
	v_mov_b32_e32 v133, v0
	v_mov_b32_e32 v134, v0
	v_mov_b32_e32 v135, v0
	v_mov_b32_e32 v140, v0
	v_mov_b32_e32 v141, v0
	v_mov_b32_e32 v142, v0
	v_mov_b32_e32 v143, v0
	v_mov_b32_e32 v72, v0
	v_mov_b32_e32 v73, v0
	v_mov_b32_e32 v74, v0
	v_mov_b32_e32 v75, v0
	v_mov_b32_e32 v76, v0
	v_mov_b32_e32 v77, v0
	v_mov_b32_e32 v78, v0
	v_mov_b32_e32 v79, v0
	v_mov_b32_e32 v104, v0
	v_mov_b32_e32 v105, v0
	v_mov_b32_e32 v106, v0
	v_mov_b32_e32 v107, v0
	v_mov_b32_e32 v108, v0
	v_mov_b32_e32 v109, v0
	v_mov_b32_e32 v110, v0
	v_mov_b32_e32 v111, v0
	v_mov_b32_e32 v120, v0
	v_mov_b32_e32 v121, v0
	v_mov_b32_e32 v122, v0
	v_mov_b32_e32 v123, v0
	v_mov_b32_e32 v124, v0
	v_mov_b32_e32 v125, v0
	v_mov_b32_e32 v126, v0
	v_mov_b32_e32 v127, v0
	v_mov_b32_e32 v144, v0
	v_mov_b32_e32 v145, v0
	v_mov_b32_e32 v146, v0
	v_mov_b32_e32 v147, v0
	v_mov_b32_e32 v148, v0
	v_mov_b32_e32 v149, v0
	v_mov_b32_e32 v150, v0
	v_mov_b32_e32 v151, v0
	.p2align	6

; template <class Epi, class Sched, bool ALIGN_EPI = false, bool SP2 = false>
; __device__ __forceinline__ void gemm_phase(PG8_LAS unsigned char* lds, const Gemm g, const Sched& S, const Epi& E) {
;     ...
;         const char* nA = has_next ? (const char*)g.A + (size_t)nxt.pm * tstepA : cA; const char* nB = has_next ? (const char*)g.Bt + (size_t)nxt.pn * tstepB : cB;
;         for (int t = 0; t < nt; t += 2) {
;             const bool last = (t == nt - 2);
;     ...
;             const char* a1 = cA + PG8_KOFFA(t + 1);
;             const char* a2 = last ? nA : cA + PG8_KOFFA(t + 2); const char* b2 = last ? nB : cB + (size_t)(t + 2) * kstep;
;             const char* a3 = last ? nA + kstep : cA + PG8_KOFFA(t + 3); const char* b3 = b2 + kstep;
;     ...
; #pragma unroll
;         for (int a = 0; a < 2; ++a)
; #pragma unroll
;             for (int b = 0; b < 2; ++b)
; #pragma unroll
;                 for (int m = 0; m < 4; ++m)
; #pragma unroll
;                     for (int n = 0; n < 2; ++n) acc[a][b][m][n] = (f32x4){0.f, 0.f, 0.f, 0.f};
.LBB0_2227:
	s_ashr_i32 s31, s30, 31
	s_lshl_b64 s[0:1], s[30:31], 20
	s_add_u32 s34, s49, s0
	s_addc_u32 s35, s50, s1
	s_and_b64 s[0:1], s[8:9], exec
	s_cselect_b32 s0, s35, s11
	s_cselect_b32 s1, s34, s10
	s_ashr_i32 s29, s28, 31
	s_lshl_b64 s[4:5], s[28:29], 20
	s_add_u32 s36, s51, s4
	s_addc_u32 s37, s52, s5
	s_and_b64 s[4:5], s[8:9], exec
	s_cselect_b32 s4, s37, s41
	s_cselect_b32 s5, s36, s40
	s_add_u32 s29, s1, 0x80
	s_addc_u32 s31, s0, 0
	s_add_u32 s39, s40, 0x100
	v_mov_b32_e32 v0, 0
	s_addc_u32 s73, s41, 0
	s_mov_b32 s76, -2
	s_mov_b32 s77, 0x18000
	s_mov_b64 s[40:41], 0
	s_waitcnt lgkmcnt(0)
	v_mov_b32_e32 v1, v0
	v_mov_b32_e32 v2, v0
	v_mov_b32_e32 v3, v0
	v_mov_b32_e32 v4, v0
	v_mov_b32_e32 v5, v0
	v_mov_b32_e32 v6, v0
	v_mov_b32_e32 v7, v0
	s_waitcnt vmcnt(21)
	v_mov_b32_e32 v16, v0
	v_mov_b32_e32 v17, v0
	s_waitcnt vmcnt(20)
	v_mov_b32_e32 v18, v0
	v_mov_b32_e32 v19, v0
	v_mov_b32_e32 v20, v0
	v_mov_b32_e32 v21, v0
	s_waitcnt vmcnt(19)
	v_mov_b32_e32 v22, v0
	v_mov_b32_e32 v23, v0
	s_waitcnt vmcnt(17)
	v_mov_b32_e32 v32, v0
	v_mov_b32_e32 v33, v0
	s_waitcnt vmcnt(16)
	v_mov_b32_e32 v34, v0
	v_mov_b32_e32 v35, v0
	v_mov_b32_e32 v36, v0
	v_mov_b32_e32 v37, v0
	s_waitcnt vmcnt(15)
	v_mov_b32_e32 v38, v0
	v_mov_b32_e32 v39, v0
	s_waitcnt vmcnt(13)
	v_mov_b32_e32 v48, v0
	v_mov_b32_e32 v49, v0
	s_waitcnt vmcnt(12)
	v_mov_b32_e32 v50, v0
	v_mov_b32_e32 v51, v0
	v_mov_b32_e32 v52, v0
	v_mov_b32_e32 v53, v0
	s_waitcnt vmcnt(11)
	v_mov_b32_e32 v54, v0
	v_mov_b32_e32 v55, v0
	v_mov_b32_e32 v8, v0
	v_mov_b32_e32 v9, v0
	v_mov_b32_e32 v10, v0
	v_mov_b32_e32 v11, v0
	v_mov_b32_e32 v12, v0
	v_mov_b32_e32 v13, v0
	v_mov_b32_e32 v14, v0
	v_mov_b32_e32 v15, v0
	v_mov_b32_e32 v24, v0
	v_mov_b32_e32 v25, v0
	v_mov_b32_e32 v26, v0
	v_mov_b32_e32 v27, v0
	v_mov_b32_e32 v28, v0
	v_mov_b32_e32 v29, v0
	v_mov_b32_e32 v30, v0
	v_mov_b32_e32 v31, v0
	v_mov_b32_e32 v40, v0
	v_mov_b32_e32 v41, v0
	v_mov_b32_e32 v42, v0
	v_mov_b32_e32 v43, v0
	v_mov_b32_e32 v44, v0
	v_mov_b32_e32 v45, v0
	v_mov_b32_e32 v46, v0
	v_mov_b32_e32 v47, v0
	v_mov_b32_e32 v56, v0
	v_mov_b32_e32 v57, v0
	s_waitcnt vmcnt(10)
	v_mov_b32_e32 v58, v0
	v_mov_b32_e32 v59, v0
	v_mov_b32_e32 v60, v0
	v_mov_b32_e32 v61, v0
	s_waitcnt vmcnt(9)
	v_mov_b32_e32 v62, v0
	v_mov_b32_e32 v63, v0
	v_mov_b32_e32 v64, v0
	v_mov_b32_e32 v65, v0
	s_waitcnt vmcnt(8)
	v_mov_b32_e32 v66, v0
	v_mov_b32_e32 v67, v0
	v_mov_b32_e32 v68, v0
	v_mov_b32_e32 v69, v0
	v_mov_b32_e32 v70, v0
	v_mov_b32_e32 v71, v0
	v_mov_b32_e32 v80, v0
	v_mov_b32_e32 v81, v0
	v_mov_b32_e32 v82, v0
	v_mov_b32_e32 v83, v0
	v_mov_b32_e32 v84, v0
	v_mov_b32_e32 v85, v0
	v_mov_b32_e32 v86, v0
	v_mov_b32_e32 v87, v0
	v_mov_b32_e32 v96, v0
	v_mov_b32_e32 v97, v0
	v_mov_b32_e32 v98, v0
	v_mov_b32_e32 v99, v0
	v_mov_b32_e32 v100, v0
	v_mov_b32_e32 v101, v0
	v_mov_b32_e32 v102, v0
	v_mov_b32_e32 v103, v0
	v_mov_b32_e32 v112, v0
	v_mov_b32_e32 v113, v0
	v_mov_b32_e32 v114, v0
	v_mov_b32_e32 v115, v0
	v_mov_b32_e32 v116, v0
	v_mov_b32_e32 v117, v0
	v_mov_b32_e32 v118, v0
	v_mov_b32_e32 v119, v0
	v_mov_b32_e32 v72, v0
	v_mov_b32_e32 v73, v0
	v_mov_b32_e32 v74, v0
	v_mov_b32_e32 v75, v0
	v_mov_b32_e32 v76, v0
	v_mov_b32_e32 v77, v0
	v_mov_b32_e32 v78, v0
	v_mov_b32_e32 v79, v0
	v_mov_b32_e32 v88, v0
	v_mov_b32_e32 v89, v0
	v_mov_b32_e32 v90, v0
	v_mov_b32_e32 v91, v0
	v_mov_b32_e32 v92, v0
	v_mov_b32_e32 v93, v0
	v_mov_b32_e32 v94, v0
	v_mov_b32_e32 v95, v0
	v_mov_b32_e32 v104, v0
	v_mov_b32_e32 v105, v0
	v_mov_b32_e32 v106, v0
	v_mov_b32_e32 v107, v0
	v_mov_b32_e32 v108, v0
	v_mov_b32_e32 v109, v0
	v_mov_b32_e32 v110, v0
	v_mov_b32_e32 v111, v0
	v_mov_b32_e32 v120, v0
	v_mov_b32_e32 v121, v0
	v_mov_b32_e32 v122, v0
	v_mov_b32_e32 v123, v0
	v_mov_b32_e32 v124, v0
	v_mov_b32_e32 v125, v0
	v_mov_b32_e32 v126, v0
	v_mov_b32_e32 v127, v0
	.p2align	6
